# hyena sample path: the two order-0 u-tile loads issued together (was load/wait/LDS-write twice)
# speedup vs baseline: 1.0070x; 1.0070x over previous
.LBB0_565:
	s_or_b32 s12, s0, s55
	s_or_b32 s50, s12, 0x800
	v_mov_b32_e32 v0, 0
	v_mov_b32_e32 v142, 0
	s_and_saveexec_b64 s[0:1], s[6:7]
	s_mov_b32 s13, s2
	s_mov_b32 s51, s2
	v_lshl_add_u64 v[0:1], s[12:13], 2, v[18:19]
	v_lshl_add_u64 v[142:143], s[50:51], 2, v[18:19]
	global_load_dword v0, v[0:1], off
	global_load_dword v142, v[142:143], off
	s_or_b64 exec, exec, s[0:1]
	v_lshlrev_b32_e32 v144, 2, v192
	v_bitop3_b32 v2, v144, s33, v203 bitop3:0x6c
	s_waitcnt vmcnt(0)
	ds_bpermute_b32 v1, v2, v0
	ds_bpermute_b32 v143, v2, v142
	v_bitop3_b32 v2, v144, 64, v203 bitop3:0x6c
	s_waitcnt lgkmcnt(0)
	v_add_f32_e32 v0, v0, v1
	v_add_f32_e32 v142, v142, v143
	ds_bpermute_b32 v1, v2, v0
	ds_bpermute_b32 v143, v2, v142
	v_bitop3_b32 v2, v144, 32, v203 bitop3:0x6c
	s_waitcnt lgkmcnt(0)
	v_add_f32_e32 v0, v0, v1
	v_add_f32_e32 v142, v142, v143
	ds_bpermute_b32 v1, v2, v0
	ds_bpermute_b32 v143, v2, v142
	v_bitop3_b32 v2, v144, 16, v203 bitop3:0x6c
	s_waitcnt lgkmcnt(0)
	v_add_f32_e32 v0, v0, v1
	v_add_f32_e32 v142, v142, v143
	ds_bpermute_b32 v1, v2, v0
	ds_bpermute_b32 v143, v2, v142
	v_bitop3_b32 v2, v144, 8, v203 bitop3:0x6c
	s_waitcnt lgkmcnt(0)
	v_add_f32_e32 v0, v0, v1
	v_add_f32_e32 v142, v142, v143
	ds_bpermute_b32 v1, v2, v0
	ds_bpermute_b32 v143, v2, v142
	v_bitop3_b32 v2, v144, 4, v203 bitop3:0x6c
	s_waitcnt lgkmcnt(0)
	v_add_f32_e32 v0, v0, v1
	v_add_f32_e32 v142, v142, v143
	ds_bpermute_b32 v1, v2, v0
	ds_bpermute_b32 v143, v2, v142
	s_waitcnt lgkmcnt(0)
	v_add_f32_e32 v0, v0, v1
	v_add_f32_e32 v142, v142, v143
	v_and_b32_e32 v2, 63, v192
	v_cmp_eq_u32_e32 vcc, 0, v2
	s_and_saveexec_b64 s[0:1], vcc
	v_ashrrev_i32_e32 v1, 6, v192
	v_lshl_add_u32 v1, v1, 2, 0
	v_add_u32_e32 v1, 0x24a80, v1
	ds_write_b32 v1, v0
	ds_write_b32 v1, v142 offset:32
	s_or_b64 exec, exec, s[0:1]
	s_add_i32 s0, 0, 0x24a80
	v_mov_b32_e32 v12, s0
	s_waitcnt lgkmcnt(0)
	s_barrier
	ds_read_b128 v[0:3], v12
	ds_read_b128 v[4:7], v12 offset:16
	ds_read_b128 v[8:11], v12 offset:32
	ds_read_b128 v[12:15], v12 offset:48
	s_mov_b32 s0, 0x358637bd
	s_waitcnt lgkmcnt(3)
	v_mov_b32_e32 v96, v0
	s_mov_b32 s4, 0
	s_waitcnt lgkmcnt(1)
	v_mov_b32_e32 v97, v8
	v_pk_add_f32 v[96:97], v[96:97], 0 op_sel_hi:[1,0]
	v_mov_b32_e32 v8, v1
	v_pk_add_f32 v[0:1], v[96:97], v[8:9]
	v_mov_b32_e32 v8, v2
	v_mov_b32_e32 v9, v10
	v_pk_add_f32 v[0:1], v[0:1], v[8:9]
	v_mov_b32_e32 v10, v3
	v_pk_add_f32 v[0:1], v[0:1], v[10:11]
	v_mov_b32_e32 v2, v4
	s_waitcnt lgkmcnt(0)
	v_mov_b32_e32 v3, v12
	v_pk_add_f32 v[0:1], v[0:1], v[2:3]
	v_mov_b32_e32 v12, v5
	v_pk_add_f32 v[0:1], v[0:1], v[12:13]
	v_mov_b32_e32 v2, v6
	v_mov_b32_e32 v3, v14
	v_pk_add_f32 v[0:1], v[0:1], v[2:3]
	v_mov_b32_e32 v14, v7
	v_pk_add_f32 v[0:1], v[0:1], v[14:15]
	s_movk_i32 s5, 0x5eed
	v_pk_add_f32 v[0:1], v[0:1], s[0:1] op_sel_hi:[1,0]
	s_mov_b32 s13, s4
	v_div_scale_f32 v2, s[0:1], v1, v1, 1.0
	v_rcp_f32_e32 v3, v2
	v_readlane_b32 s16, v254, 10
	v_readlane_b32 s22, v254, 16
	v_readlane_b32 s23, v254, 17
	v_fma_f32 v4, -v2, v3, 1.0
	v_fmac_f32_e32 v3, v4, v3
	v_div_scale_f32 v4, vcc, 1.0, v1, 1.0
	v_mul_f32_e32 v5, v4, v3
	v_fma_f32 v6, -v2, v5, v4
	v_fmac_f32_e32 v5, v6, v3
	v_fma_f32 v2, -v2, v5, v4
	v_div_fmas_f32 v2, v2, v3, v5
	v_div_fixup_f32 v1, v2, v1, 1.0
	v_div_scale_f32 v2, s[0:1], v0, v0, 1.0
	v_rcp_f32_e32 v3, v2
	s_lshl_b64 s[0:1], s[12:13], 2
	s_add_u32 s0, s22, s0
	s_addc_u32 s1, s23, s1
	v_fma_f32 v4, -v2, v3, 1.0
	v_fmac_f32_e32 v3, v4, v3
	v_div_scale_f32 v4, vcc, 1.0, v0, 1.0
	v_mul_f32_e32 v5, v4, v3
	v_fma_f32 v6, -v2, v5, v4
	v_fmac_f32_e32 v5, v6, v3
	v_fma_f32 v2, -v2, v5, v4
	global_load_dword v4, v112, s[0:1]
	s_lshl_b64 s[0:1], s[12:13], 14
	s_add_u32 s80, s91, s0
	s_addc_u32 s81, s54, s1
	s_lshl_b32 s0, s50, 12
	s_mov_b32 s1, s4
	s_lshl_b64 s[0:1], s[0:1], 2
	v_div_fmas_f32 v2, v2, v3, v5
	s_add_u32 s12, s91, s0
	v_div_fixup_f32 v0, v2, v0, 1.0
	s_mov_b32 s2, 0
	s_addc_u32 s13, s54, s1
	v_mov_b32_e32 v2, 0
	v_mov_b32_e32 v3, 0
	v_readlane_b32 s17, v254, 11
	v_readlane_b32 s18, v254, 12
	v_readlane_b32 s19, v254, 13
	v_readlane_b32 s20, v254, 14
	v_readlane_b32 s21, v254, 15
	v_readlane_b32 s24, v254, 18
	v_readlane_b32 s25, v254, 19
	v_readlane_b32 s26, v254, 20
	v_readlane_b32 s27, v254, 21
	v_readlane_b32 s28, v254, 22
	v_readlane_b32 s29, v254, 23
	v_readlane_b32 s30, v254, 24
	v_readlane_b32 s31, v254, 25
	s_movk_i32 s3, 0x5eed
	s_sub_u32 s0, s12, s80
	v_lshlrev_b32_e32 v248, 4, v192
	v_sub_u32_e32 v213, 0x1000, v248
	v_sub_u32_e32 v249, 0, v213
	v_max_i32_e32 v249, v213, v249
	v_ashrrev_i32_e32 v250, 31, v213
	v_and_b32_e32 v250, s0, v250
	v_lshl_add_u32 v249, v249, 2, v250
	global_load_dword v95, v249, s[80:81]
	v_add_u32_e32 v214, -1, v213
	v_sub_u32_e32 v249, 0, v214
	v_max_i32_e32 v249, v214, v249
	v_ashrrev_i32_e32 v250, 31, v214
	v_and_b32_e32 v250, s0, v250
	v_lshl_add_u32 v249, v249, 2, v250
	global_load_dword v96, v249, s[80:81]
	v_add_u32_e32 v215, -2, v213
	v_sub_u32_e32 v249, 0, v215
	v_max_i32_e32 v249, v215, v249
	v_ashrrev_i32_e32 v250, 31, v215
	v_and_b32_e32 v250, s0, v250
	v_lshl_add_u32 v249, v249, 2, v250
	global_load_dword v97, v249, s[80:81]
	v_add_u32_e32 v216, -3, v213
	v_sub_u32_e32 v249, 0, v216
	v_max_i32_e32 v249, v216, v249
	v_ashrrev_i32_e32 v250, 31, v216
	v_and_b32_e32 v250, s0, v250
	v_lshl_add_u32 v249, v249, 2, v250
	global_load_dword v98, v249, s[80:81]
	v_add_u32_e32 v217, -4, v213
	v_sub_u32_e32 v249, 0, v217
	v_max_i32_e32 v249, v217, v249
	v_ashrrev_i32_e32 v250, 31, v217
	v_and_b32_e32 v250, s0, v250
	v_lshl_add_u32 v249, v249, 2, v250
	global_load_dword v99, v249, s[80:81]
	v_add_u32_e32 v218, -5, v213
	v_sub_u32_e32 v249, 0, v218
	v_max_i32_e32 v249, v218, v249
	v_ashrrev_i32_e32 v250, 31, v218
	v_and_b32_e32 v250, s0, v250
	v_lshl_add_u32 v249, v249, 2, v250
	global_load_dword v100, v249, s[80:81]
	v_add_u32_e32 v219, -6, v213
	v_sub_u32_e32 v249, 0, v219
	v_max_i32_e32 v249, v219, v249
	v_ashrrev_i32_e32 v250, 31, v219
	v_and_b32_e32 v250, s0, v250
	v_lshl_add_u32 v249, v249, 2, v250
	global_load_dword v101, v249, s[80:81]
	v_add_u32_e32 v220, -7, v213
	v_sub_u32_e32 v249, 0, v220
	v_max_i32_e32 v249, v220, v249
	v_ashrrev_i32_e32 v250, 31, v220
	v_and_b32_e32 v250, s0, v250
	v_lshl_add_u32 v249, v249, 2, v250
	global_load_dword v102, v249, s[80:81]
	v_add_u32_e32 v221, -8, v213
	v_sub_u32_e32 v249, 0, v221
	v_max_i32_e32 v249, v221, v249
	v_ashrrev_i32_e32 v250, 31, v221
	v_and_b32_e32 v250, s0, v250
	v_lshl_add_u32 v249, v249, 2, v250
	global_load_dword v103, v249, s[80:81]
	v_add_u32_e32 v222, -9, v213
	v_sub_u32_e32 v249, 0, v222
	v_max_i32_e32 v249, v222, v249
	v_ashrrev_i32_e32 v250, 31, v222
	v_and_b32_e32 v250, s0, v250
	v_lshl_add_u32 v249, v249, 2, v250
	global_load_dword v104, v249, s[80:81]
	v_add_u32_e32 v223, -10, v213
	v_sub_u32_e32 v249, 0, v223
	v_max_i32_e32 v249, v223, v249
	v_ashrrev_i32_e32 v250, 31, v223
	v_and_b32_e32 v250, s0, v250
	v_lshl_add_u32 v249, v249, 2, v250
	global_load_dword v105, v249, s[80:81]
	v_add_u32_e32 v224, -11, v213
	v_sub_u32_e32 v249, 0, v224
	v_max_i32_e32 v249, v224, v249
	v_ashrrev_i32_e32 v250, 31, v224
	v_and_b32_e32 v250, s0, v250
	v_lshl_add_u32 v249, v249, 2, v250
	global_load_dword v106, v249, s[80:81]
	v_add_u32_e32 v225, -12, v213
	v_sub_u32_e32 v249, 0, v225
	v_max_i32_e32 v249, v225, v249
	v_ashrrev_i32_e32 v250, 31, v225
	v_and_b32_e32 v250, s0, v250
	v_lshl_add_u32 v249, v249, 2, v250
	global_load_dword v107, v249, s[80:81]
	v_add_u32_e32 v226, -13, v213
	v_sub_u32_e32 v249, 0, v226
	v_max_i32_e32 v249, v226, v249
	v_ashrrev_i32_e32 v250, 31, v226
	v_and_b32_e32 v250, s0, v250
	v_lshl_add_u32 v249, v249, 2, v250
	global_load_dword v108, v249, s[80:81]
	v_add_u32_e32 v227, -14, v213
	v_sub_u32_e32 v249, 0, v227
	v_max_i32_e32 v249, v227, v249
	v_ashrrev_i32_e32 v250, 31, v227
	v_and_b32_e32 v250, s0, v250
	v_lshl_add_u32 v249, v249, 2, v250
	global_load_dword v109, v249, s[80:81]
	v_add_u32_e32 v228, -15, v213
	v_sub_u32_e32 v249, 0, v228
	v_max_i32_e32 v249, v228, v249
	v_ashrrev_i32_e32 v250, 31, v228
	v_and_b32_e32 v250, s0, v250
	v_lshl_add_u32 v249, v249, 2, v250
	global_load_dword v110, v249, s[80:81]
	v_add_u32_e32 v229, -16, v213
	v_sub_u32_e32 v249, 0, v229
	v_max_i32_e32 v249, v229, v249
	v_ashrrev_i32_e32 v250, 31, v229
	v_and_b32_e32 v250, s0, v250
	v_lshl_add_u32 v249, v249, 2, v250
	global_load_dword v111, v249, s[80:81]
	v_add_u32_e32 v230, -17, v213
	v_sub_u32_e32 v249, 0, v230
	v_max_i32_e32 v249, v230, v249
	v_ashrrev_i32_e32 v250, 31, v230
	v_and_b32_e32 v250, s0, v250
	v_lshl_add_u32 v249, v249, 2, v250
	global_load_dword v122, v249, s[80:81]
	v_add_u32_e32 v231, -18, v213
	v_sub_u32_e32 v249, 0, v231
	v_max_i32_e32 v249, v231, v249
	v_ashrrev_i32_e32 v250, 31, v231
	v_and_b32_e32 v250, s0, v250
	v_lshl_add_u32 v249, v249, 2, v250
	global_load_dword v123, v249, s[80:81]
	v_add_u32_e32 v232, -19, v213
	v_sub_u32_e32 v249, 0, v232
	v_max_i32_e32 v249, v232, v249
	v_ashrrev_i32_e32 v250, 31, v232
	v_and_b32_e32 v250, s0, v250
	v_lshl_add_u32 v249, v249, 2, v250
	global_load_dword v124, v249, s[80:81]
	v_add_u32_e32 v233, -20, v213
	v_sub_u32_e32 v249, 0, v233
	v_max_i32_e32 v249, v233, v249
	v_ashrrev_i32_e32 v250, 31, v233
	v_and_b32_e32 v250, s0, v250
	v_lshl_add_u32 v249, v249, 2, v250
	global_load_dword v125, v249, s[80:81]
	v_add_u32_e32 v234, -21, v213
	v_sub_u32_e32 v249, 0, v234
	v_max_i32_e32 v249, v234, v249
	v_ashrrev_i32_e32 v250, 31, v234
	v_and_b32_e32 v250, s0, v250
	v_lshl_add_u32 v249, v249, 2, v250
	global_load_dword v126, v249, s[80:81]
	v_add_u32_e32 v235, -22, v213
	v_sub_u32_e32 v249, 0, v235
	v_max_i32_e32 v249, v235, v249
	v_ashrrev_i32_e32 v250, 31, v235
	v_and_b32_e32 v250, s0, v250
	v_lshl_add_u32 v249, v249, 2, v250
	global_load_dword v127, v249, s[80:81]
	global_load_dword v246, v112, s[80:81]
	global_load_dword v247, v112, s[12:13]
	v_lshlrev_b32_e32 v251, 5, v192
	v_add_u32_e32 v162, 0x100d0, v251
	s_waitcnt vmcnt(0)
	v_mul_f32_e32 v246, v0, v246
	v_mul_f32_e32 v247, v1, v247
	v_add_f32_e32 v246, v246, v247
	v_add_f32_e32 v246, v4, v246
	v_cmp_lt_i32_e32 vcc, 0, v213
	v_add_u32_e32 v249, 0xfff, v213
	s_nop 0
	v_cndmask_b32_e32 v248, v1, v0, vcc
	v_cmp_eq_u32_e32 vcc, 0, v213
	v_mul_f32_e32 v95, v248, v95
	s_nop 0
	v_cndmask_b32_e32 v95, v95, v246, vcc
	v_cmp_gt_u32_e32 vcc, 0x1fff, v249
	s_nop 1
	v_cndmask_b32_e32 v95, 0, v95, vcc
	v_cmp_lt_i32_e32 vcc, 0, v214
	v_add_u32_e32 v249, 0xfff, v214
	s_nop 0
	v_cndmask_b32_e32 v248, v1, v0, vcc
	v_cmp_eq_u32_e32 vcc, 0, v214
	v_mul_f32_e32 v96, v248, v96
	s_nop 0
	v_cndmask_b32_e32 v96, v96, v246, vcc
	v_cmp_gt_u32_e32 vcc, 0x1fff, v249
	s_nop 1
	v_cndmask_b32_e32 v96, 0, v96, vcc
	v_cmp_lt_i32_e32 vcc, 0, v215
	v_add_u32_e32 v249, 0xfff, v215
	s_nop 0
	v_cndmask_b32_e32 v248, v1, v0, vcc
	v_cmp_eq_u32_e32 vcc, 0, v215
	v_mul_f32_e32 v97, v248, v97
	s_nop 0
	v_cndmask_b32_e32 v97, v97, v246, vcc
	v_cmp_gt_u32_e32 vcc, 0x1fff, v249
	s_nop 1
	v_cndmask_b32_e32 v97, 0, v97, vcc
	v_cmp_lt_i32_e32 vcc, 0, v216
	v_add_u32_e32 v249, 0xfff, v216
	s_nop 0
	v_cndmask_b32_e32 v248, v1, v0, vcc
	v_cmp_eq_u32_e32 vcc, 0, v216
	v_mul_f32_e32 v98, v248, v98
	s_nop 0
	v_cndmask_b32_e32 v98, v98, v246, vcc
	v_cmp_gt_u32_e32 vcc, 0x1fff, v249
	s_nop 1
	v_cndmask_b32_e32 v98, 0, v98, vcc
	v_cmp_lt_i32_e32 vcc, 0, v217
	v_add_u32_e32 v249, 0xfff, v217
	s_nop 0
	v_cndmask_b32_e32 v248, v1, v0, vcc
	v_cmp_eq_u32_e32 vcc, 0, v217
	v_mul_f32_e32 v99, v248, v99
	s_nop 0
	v_cndmask_b32_e32 v99, v99, v246, vcc
	v_cmp_gt_u32_e32 vcc, 0x1fff, v249
	s_nop 1
	v_cndmask_b32_e32 v99, 0, v99, vcc
	v_cmp_lt_i32_e32 vcc, 0, v218
	v_add_u32_e32 v249, 0xfff, v218
	s_nop 0
	v_cndmask_b32_e32 v248, v1, v0, vcc
	v_cmp_eq_u32_e32 vcc, 0, v218
	v_mul_f32_e32 v100, v248, v100
	s_nop 0
	v_cndmask_b32_e32 v100, v100, v246, vcc
	v_cmp_gt_u32_e32 vcc, 0x1fff, v249
	s_nop 1
	v_cndmask_b32_e32 v100, 0, v100, vcc
	v_cmp_lt_i32_e32 vcc, 0, v219
	v_add_u32_e32 v249, 0xfff, v219
	s_nop 0
	v_cndmask_b32_e32 v248, v1, v0, vcc
	v_cmp_eq_u32_e32 vcc, 0, v219
	v_mul_f32_e32 v101, v248, v101
	s_nop 0
	v_cndmask_b32_e32 v101, v101, v246, vcc
	v_cmp_gt_u32_e32 vcc, 0x1fff, v249
	s_nop 1
	v_cndmask_b32_e32 v101, 0, v101, vcc
	v_cmp_lt_i32_e32 vcc, 0, v220
	v_add_u32_e32 v249, 0xfff, v220
	s_nop 0
	v_cndmask_b32_e32 v248, v1, v0, vcc
	v_cmp_eq_u32_e32 vcc, 0, v220
	v_mul_f32_e32 v102, v248, v102
	s_nop 0
	v_cndmask_b32_e32 v102, v102, v246, vcc
	v_cmp_gt_u32_e32 vcc, 0x1fff, v249
	s_nop 1
	v_cndmask_b32_e32 v102, 0, v102, vcc
	v_cmp_lt_i32_e32 vcc, 0, v221
	v_add_u32_e32 v249, 0xfff, v221
	s_nop 0
	v_cndmask_b32_e32 v248, v1, v0, vcc
	v_cmp_eq_u32_e32 vcc, 0, v221
	v_mul_f32_e32 v103, v248, v103
	s_nop 0
	v_cndmask_b32_e32 v103, v103, v246, vcc
	v_cmp_gt_u32_e32 vcc, 0x1fff, v249
	s_nop 1
	v_cndmask_b32_e32 v103, 0, v103, vcc
	v_cmp_lt_i32_e32 vcc, 0, v222
	v_add_u32_e32 v249, 0xfff, v222
	s_nop 0
	v_cndmask_b32_e32 v248, v1, v0, vcc
	v_cmp_eq_u32_e32 vcc, 0, v222
	v_mul_f32_e32 v104, v248, v104
	s_nop 0
	v_cndmask_b32_e32 v104, v104, v246, vcc
	v_cmp_gt_u32_e32 vcc, 0x1fff, v249
	s_nop 1
	v_cndmask_b32_e32 v104, 0, v104, vcc
	v_cmp_lt_i32_e32 vcc, 0, v223
	v_add_u32_e32 v249, 0xfff, v223
	s_nop 0
	v_cndmask_b32_e32 v248, v1, v0, vcc
	v_cmp_eq_u32_e32 vcc, 0, v223
	v_mul_f32_e32 v105, v248, v105
	s_nop 0
	v_cndmask_b32_e32 v105, v105, v246, vcc
	v_cmp_gt_u32_e32 vcc, 0x1fff, v249
	s_nop 1
	v_cndmask_b32_e32 v105, 0, v105, vcc
	v_cmp_lt_i32_e32 vcc, 0, v224
	v_add_u32_e32 v249, 0xfff, v224
	s_nop 0
	v_cndmask_b32_e32 v248, v1, v0, vcc
	v_cmp_eq_u32_e32 vcc, 0, v224
	v_mul_f32_e32 v106, v248, v106
	s_nop 0
	v_cndmask_b32_e32 v106, v106, v246, vcc
	v_cmp_gt_u32_e32 vcc, 0x1fff, v249
	s_nop 1
	v_cndmask_b32_e32 v106, 0, v106, vcc
	v_cmp_lt_i32_e32 vcc, 0, v225
	v_add_u32_e32 v249, 0xfff, v225
	s_nop 0
	v_cndmask_b32_e32 v248, v1, v0, vcc
	v_cmp_eq_u32_e32 vcc, 0, v225
	v_mul_f32_e32 v107, v248, v107
	s_nop 0
	v_cndmask_b32_e32 v107, v107, v246, vcc
	v_cmp_gt_u32_e32 vcc, 0x1fff, v249
	s_nop 1
	v_cndmask_b32_e32 v107, 0, v107, vcc
	v_cmp_lt_i32_e32 vcc, 0, v226
	v_add_u32_e32 v249, 0xfff, v226
	s_nop 0
	v_cndmask_b32_e32 v248, v1, v0, vcc
	v_cmp_eq_u32_e32 vcc, 0, v226
	v_mul_f32_e32 v108, v248, v108
	s_nop 0
	v_cndmask_b32_e32 v108, v108, v246, vcc
	v_cmp_gt_u32_e32 vcc, 0x1fff, v249
	s_nop 1
	v_cndmask_b32_e32 v108, 0, v108, vcc
	v_cmp_lt_i32_e32 vcc, 0, v227
	v_add_u32_e32 v249, 0xfff, v227
	s_nop 0
	v_cndmask_b32_e32 v248, v1, v0, vcc
	v_cmp_eq_u32_e32 vcc, 0, v227
	v_mul_f32_e32 v109, v248, v109
	s_nop 0
	v_cndmask_b32_e32 v109, v109, v246, vcc
	v_cmp_gt_u32_e32 vcc, 0x1fff, v249
	s_nop 1
	v_cndmask_b32_e32 v109, 0, v109, vcc
	v_cmp_lt_i32_e32 vcc, 0, v228
	v_add_u32_e32 v249, 0xfff, v228
	s_nop 0
	v_cndmask_b32_e32 v248, v1, v0, vcc
	v_cmp_eq_u32_e32 vcc, 0, v228
	v_mul_f32_e32 v110, v248, v110
	s_nop 0
	v_cndmask_b32_e32 v110, v110, v246, vcc
	v_cmp_gt_u32_e32 vcc, 0x1fff, v249
	s_nop 1
	v_cndmask_b32_e32 v110, 0, v110, vcc
	v_cmp_lt_i32_e32 vcc, 0, v229
	v_add_u32_e32 v249, 0xfff, v229
	s_nop 0
	v_cndmask_b32_e32 v248, v1, v0, vcc
	v_cmp_eq_u32_e32 vcc, 0, v229
	v_mul_f32_e32 v111, v248, v111
	s_nop 0
	v_cndmask_b32_e32 v111, v111, v246, vcc
	v_cmp_gt_u32_e32 vcc, 0x1fff, v249
	s_nop 1
	v_cndmask_b32_e32 v111, 0, v111, vcc
	v_cmp_lt_i32_e32 vcc, 0, v230
	v_add_u32_e32 v249, 0xfff, v230
	s_nop 0
	v_cndmask_b32_e32 v248, v1, v0, vcc
	v_cmp_eq_u32_e32 vcc, 0, v230
	v_mul_f32_e32 v122, v248, v122
	s_nop 0
	v_cndmask_b32_e32 v122, v122, v246, vcc
	v_cmp_gt_u32_e32 vcc, 0x1fff, v249
	s_nop 1
	v_cndmask_b32_e32 v122, 0, v122, vcc
	v_cmp_lt_i32_e32 vcc, 0, v231
	v_add_u32_e32 v249, 0xfff, v231
	s_nop 0
	v_cndmask_b32_e32 v248, v1, v0, vcc
	v_cmp_eq_u32_e32 vcc, 0, v231
	v_mul_f32_e32 v123, v248, v123
	s_nop 0
	v_cndmask_b32_e32 v123, v123, v246, vcc
	v_cmp_gt_u32_e32 vcc, 0x1fff, v249
	s_nop 1
	v_cndmask_b32_e32 v123, 0, v123, vcc
	v_cmp_lt_i32_e32 vcc, 0, v232
	v_add_u32_e32 v249, 0xfff, v232
	s_nop 0
	v_cndmask_b32_e32 v248, v1, v0, vcc
	v_cmp_eq_u32_e32 vcc, 0, v232
	v_mul_f32_e32 v124, v248, v124
	s_nop 0
	v_cndmask_b32_e32 v124, v124, v246, vcc
	v_cmp_gt_u32_e32 vcc, 0x1fff, v249
	s_nop 1
	v_cndmask_b32_e32 v124, 0, v124, vcc
	v_cmp_lt_i32_e32 vcc, 0, v233
	v_add_u32_e32 v249, 0xfff, v233
	s_nop 0
	v_cndmask_b32_e32 v248, v1, v0, vcc
	v_cmp_eq_u32_e32 vcc, 0, v233
	v_mul_f32_e32 v125, v248, v125
	s_nop 0
	v_cndmask_b32_e32 v125, v125, v246, vcc
	v_cmp_gt_u32_e32 vcc, 0x1fff, v249
	s_nop 1
	v_cndmask_b32_e32 v125, 0, v125, vcc
	v_cmp_lt_i32_e32 vcc, 0, v234
	v_add_u32_e32 v249, 0xfff, v234
	s_nop 0
	v_cndmask_b32_e32 v248, v1, v0, vcc
	v_cmp_eq_u32_e32 vcc, 0, v234
	v_mul_f32_e32 v126, v248, v126
	s_nop 0
	v_cndmask_b32_e32 v126, v126, v246, vcc
	v_cmp_gt_u32_e32 vcc, 0x1fff, v249
	s_nop 1
	v_cndmask_b32_e32 v126, 0, v126, vcc
	v_cmp_lt_i32_e32 vcc, 0, v235
	v_add_u32_e32 v249, 0xfff, v235
	s_nop 0
	v_cndmask_b32_e32 v248, v1, v0, vcc
	v_cmp_eq_u32_e32 vcc, 0, v235
	v_mul_f32_e32 v127, v248, v127
	s_nop 0
	v_cndmask_b32_e32 v127, v127, v246, vcc
	v_cmp_gt_u32_e32 vcc, 0x1fff, v249
	s_nop 1
	v_cndmask_b32_e32 v127, 0, v127, vcc
	v_cvt_pk_bf16_f32 v142, v95, v96
	v_cvt_pk_bf16_f32 v143, v97, v98
	v_cvt_pk_bf16_f32 v144, v99, v100
	v_cvt_pk_bf16_f32 v145, v101, v102
	v_cvt_pk_bf16_f32 v146, v103, v104
	v_cvt_pk_bf16_f32 v147, v105, v106
	v_cvt_pk_bf16_f32 v148, v107, v108
	v_cvt_pk_bf16_f32 v149, v109, v110
	v_cvt_pk_bf16_f32 v150, v111, v122
	v_cvt_pk_bf16_f32 v151, v123, v124
	v_cvt_pk_bf16_f32 v152, v97, v98
	v_cvt_pk_bf16_f32 v153, v99, v100
	v_cvt_pk_bf16_f32 v154, v101, v102
	v_cvt_pk_bf16_f32 v155, v103, v104
	v_cvt_pk_bf16_f32 v156, v105, v106
	v_cvt_pk_bf16_f32 v157, v107, v108
	v_cvt_pk_bf16_f32 v158, v109, v110
	v_cvt_pk_bf16_f32 v159, v111, v122
	v_cvt_pk_bf16_f32 v160, v123, v124
	v_cvt_pk_bf16_f32 v161, v125, v126
	v_cvt_pk_bf16_f32 v236, v96, v97
	v_cvt_pk_bf16_f32 v237, v98, v99
	v_cvt_pk_bf16_f32 v238, v100, v101
	v_cvt_pk_bf16_f32 v239, v102, v103
	v_cvt_pk_bf16_f32 v240, v104, v105
	v_cvt_pk_bf16_f32 v241, v106, v107
	v_cvt_pk_bf16_f32 v242, v108, v109
	v_cvt_pk_bf16_f32 v243, v110, v111
	v_cvt_pk_bf16_f32 v244, v122, v123
	v_cvt_pk_bf16_f32 v245, v124, v125
	v_cvt_pk_bf16_f32 v170, v98, v99
	v_cvt_pk_bf16_f32 v171, v100, v101
	v_cvt_pk_bf16_f32 v172, v102, v103
	v_cvt_pk_bf16_f32 v173, v104, v105
	v_cvt_pk_bf16_f32 v174, v106, v107
	v_cvt_pk_bf16_f32 v175, v108, v109
	v_cvt_pk_bf16_f32 v176, v110, v111
	v_cvt_pk_bf16_f32 v177, v122, v123
	v_cvt_pk_bf16_f32 v178, v124, v125
	v_cvt_pk_bf16_f32 v179, v126, v127
	ds_write_b128 v251, v[142:145] offset:0
	ds_write_b128 v251, v[146:149] offset:16
	ds_write_b128 v251, v[236:239] offset:16400
	ds_write_b128 v251, v[240:243] offset:16416
	ds_write_b128 v251, v[152:155] offset:32848
	ds_write_b128 v251, v[156:159] offset:32864
	ds_write_b128 v251, v[170:173] offset:49296
	ds_write_b128 v251, v[174:177] offset:49312
	ds_write_b128 v162, v[144:147] offset:0
	ds_write_b128 v162, v[148:151] offset:16
	ds_write_b128 v162, v[238:241] offset:16512
	ds_write_b128 v162, v[242:245] offset:16528
	ds_write_b128 v162, v[154:157] offset:32960
	ds_write_b128 v162, v[158:161] offset:32976
	ds_write_b128 v162, v[172:175] offset:49408
	ds_write_b128 v162, v[176:179] offset:49424
	s_andn2_b64 vcc, exec, s[88:89]
	s_cbranch_vccnz .LBB0_721
	global_load_dwordx4 v[0:3], v[56:57], off
	global_load_dwordx4 v[4:7], v[58:59], off
	v_add_u32_e32 v8, v17, v67
	v_add_u32_e32 v9, v17, v66
	s_waitcnt vmcnt(1)
	ds_write_b128 v8, v[0:3]
	s_waitcnt vmcnt(0)
	ds_write_b128 v9, v[4:7]
